# conv phase: once-read A/G row stream (LDS-DMA ring loads) marked nt (cache-policy hint)
# speedup vs baseline: 1.0071x; 1.0022x over previous
; __device__ __forceinline__ float bflo(unsigned w) { return __uint_as_float(w << 16); }
; __device__ __forceinline__ float bfhi(unsigned w) { return __uint_as_float(w & 0xffff0000u); }
; __device__ __forceinline__ void phase_conv(const Ctx& P, int L) {
;     ...
;     for (int it = P.bid * NTHREADS + P.tid; it < (MP / 16) * (DFF / 8); it += P.nb * NTHREADS) {
;         const int rb = it / (DFF / 8), cc = it % (DFF / 8), row0 = rb * 16, c0 = cc * 8;
;         if (row0 >= TT) { const u32x4 z = {0u, 0u, 0u, 0u}; for (int r = 0; r < 16; ++r) *(u32x4*)(U + (size_t)(row0 + r) * DFF + c0) = z; continue; }
;         float w0[8], w1[8], w2[8], bb[8], am2[8], am1[8];
; #pragma unroll
;         for (int q = 0; q < 2; ++q) { const f32x4 a = *(const f32x4*)(cw + c0 + 4 * q), b = *(const f32x4*)(cw + DFF + c0 + 4 * q), c = *(const f32x4*)(cw + 2 * DFF + c0 + 4 * q), d = *(const f32x4*)(cb + c0 + 4 * q);
; #pragma unroll
;             for (int j = 0; j < 4; ++j) { w0[4 * q + j] = a[j]; w1[4 * q + j] = b[j]; w2[4 * q + j] = c[j]; bb[4 * q + j] = d[j]; } }
;         const bool sample = row0 >= TP;
; #pragma unroll
;         for (int j = 0; j < 8; ++j) { am2[j] = 0.f; am1[j] = 0.f; }
;         if (!sample && (row0 & (SEQ - 1)) != 0) {
;             const u32x4 p2 = *(const u32x4*)(AB + (size_t)(row0 - 2) * DFF + c0), p1 = *(const u32x4*)(AB + (size_t)(row0 - 1) * DFF + c0);
; #pragma unroll
;             for (int j = 0; j < 4; ++j) { am2[2 * j] = bflo(p2[j]); am2[2 * j + 1] = bfhi(p2[j]); am1[2 * j] = bflo(p1[j]); am1[2 * j + 1] = bfhi(p1[j]); } }
;         for (int r = 0; r < 16; ++r) { const int row = row0 + r;
;             if (sample && (r & 3) == 0) { const int b = (row - TP) >> 2; const float* sp = P.in[I_SCONV] + ((size_t)(L * 32 + b) * 2) * DFF + c0;
; #pragma unroll
;                 for (int q = 0; q < 2; ++q) { const f32x4 s0 = *(const f32x4*)(sp + 4 * q), s1 = *(const f32x4*)(sp + DFF + 4 * q);
; #pragma unroll
;                     for (int j = 0; j < 4; ++j) { am2[4 * q + j] = s0[j]; am1[4 * q + j] = s1[j]; } } }
;             const u32x4 aw = *(const u32x4*)(AB + (size_t)row * DFF + c0), gw = *(const u32x4*)(GB + (size_t)row * DFF + c0);
.LBB0_189:
	s_or_b64 exec, exec, s[54:55]
	v_ashrrev_i32_e32 v46, 8, v45
	s_mov_b64 s[54:55], 0x1bf0000
	v_add_u32_e32 v46, s13, v46
	v_lshl_add_u64 v[50:51], v[40:41], 0, s[54:55]
	s_mov_b64 s[54:55], 0x1c06000
	v_readlane_b32 s72, v254, 51
	s_movk_i32 s24, 0x2c00
	v_mov_b32_e32 v128, v40
	v_ashrrev_i32_e32 v47, 31, v46
	v_lshl_add_u64 v[52:53], v[40:41], 0, s[54:55]
	v_readlane_b32 s86, v252, 1
	v_readlane_b32 s87, v252, 2
	s_waitcnt vmcnt(4)
	v_mov_b32_e32 v62, v8
	s_waitcnt vmcnt(2)
	v_mov_b32_e32 v63, v28
	v_mov_b32_e32 v28, v9
	v_mad_i64_i32 v[8:9], s[54:55], v44, s24, v[42:43]
	v_lshlrev_b64 v[48:49], 1, v[46:47]
	v_lshl_add_u64 v[54:55], v[128:129], 2, s[86:87]
	v_mov_b32_e32 v56, v14
	v_mov_b32_e32 v57, v26
	v_mov_b32_e32 v26, v15
	v_mov_b32_e32 v58, v12
	v_mov_b32_e32 v59, v24
	v_mov_b32_e32 v24, v13
	v_mov_b32_e32 v60, v10
	v_mov_b32_e32 v61, v30
	v_mov_b32_e32 v30, v11
	v_add_u32_e32 v75, 0xffffe000, v44
	v_lshlrev_b32_sdwa v76, v167, v45 dst_sel:DWORD dst_unused:UNUSED_PAD src0_sel:DWORD src1_sel:BYTE_0
	v_lshl_add_u64 v[64:65], s[40:41], 0, v[8:9]
	v_lshrrev_b32_e32 v90, 6, v179
	v_and_b32_e32 v91, 63, v179
	v_lshlrev_b32_e32 v90, 14, v90
	s_mov_b32 s56, 0x2c00
	s_mov_b32 s57, 0
	v_lshl_add_u32 v91, v91, 4, v90
	s_mov_b32 s54, 0x5ac0000
	s_mov_b32 s55, 0
	v_readfirstlane_b32 s60, v90
	v_mov_b64_e32 v[92:93], v[64:65]
	v_lshl_add_u64 v[96:97], v[64:65], 0, s[54:55]
	s_mov_b32 m0, s60
	s_nop 0
	global_load_lds_dwordx4 v[92:93], off nt
	s_add_i32 m0, s60, 0x400
	v_lshl_add_u64 v[92:93], v[92:93], 0, s[56:57]
	global_load_lds_dwordx4 v[96:97], off nt
	v_lshl_add_u64 v[96:97], v[96:97], 0, s[56:57]
	s_add_i32 m0, s60, 0x800
	s_nop 0
	global_load_lds_dwordx4 v[92:93], off nt
	s_add_i32 m0, s60, 0xc00
	v_lshl_add_u64 v[92:93], v[92:93], 0, s[56:57]
	global_load_lds_dwordx4 v[96:97], off nt
	v_lshl_add_u64 v[96:97], v[96:97], 0, s[56:57]
	s_add_i32 m0, s60, 0x1000
	s_nop 0
	global_load_lds_dwordx4 v[92:93], off nt
	s_add_i32 m0, s60, 0x1400
	v_lshl_add_u64 v[92:93], v[92:93], 0, s[56:57]
	global_load_lds_dwordx4 v[96:97], off nt
	v_lshl_add_u64 v[96:97], v[96:97], 0, s[56:57]
	s_add_i32 m0, s60, 0x1800
	s_nop 0
	global_load_lds_dwordx4 v[92:93], off nt
	s_add_i32 m0, s60, 0x1c00
	v_lshl_add_u64 v[92:93], v[92:93], 0, s[56:57]
	global_load_lds_dwordx4 v[96:97], off nt
	v_lshl_add_u64 v[96:97], v[96:97], 0, s[56:57]
	s_add_i32 m0, s60, 0x2000
	s_nop 0
	global_load_lds_dwordx4 v[92:93], off nt
	s_add_i32 m0, s60, 0x2400
	v_lshl_add_u64 v[92:93], v[92:93], 0, s[56:57]
	global_load_lds_dwordx4 v[96:97], off nt
	v_lshl_add_u64 v[96:97], v[96:97], 0, s[56:57]
	s_add_i32 m0, s60, 0x2800
	s_nop 0
	global_load_lds_dwordx4 v[92:93], off nt
	s_add_i32 m0, s60, 0x2c00
	v_lshl_add_u64 v[92:93], v[92:93], 0, s[56:57]
	global_load_lds_dwordx4 v[96:97], off nt
	v_lshl_add_u64 v[96:97], v[96:97], 0, s[56:57]
	s_add_i32 m0, s60, 0x3000
	s_nop 0
	global_load_lds_dwordx4 v[92:93], off nt
	s_add_i32 m0, s60, 0x3400
	v_lshl_add_u64 v[92:93], v[92:93], 0, s[56:57]
	global_load_lds_dwordx4 v[96:97], off nt
	v_lshl_add_u64 v[96:97], v[96:97], 0, s[56:57]
	s_add_i32 m0, s60, 0x3800
	s_nop 0
	global_load_lds_dwordx4 v[92:93], off nt
	s_add_i32 m0, s60, 0x3c00
	s_nop 0
	global_load_lds_dwordx4 v[96:97], off nt
	s_mov_b32 s24, 0
	v_readlane_b32 s73, v254, 52
	v_readlane_b32 s74, v254, 53
	v_readlane_b32 s75, v254, 54
	v_readlane_b32 s76, v254, 55
	v_readlane_b32 s77, v254, 56
	v_readlane_b32 s78, v254, 57
	v_readlane_b32 s79, v254, 58
	v_readlane_b32 s80, v254, 59
	v_readlane_b32 s81, v254, 60
	v_readlane_b32 s82, v254, 61
	v_readlane_b32 s83, v254, 62
	v_readlane_b32 s84, v254, 63
	v_readlane_b32 s85, v252, 0
	s_branch .LBB0_191

; __device__ __forceinline__ void phase_conv(const Ctx& P, int L) {
;     ...
;         for (int r = 0; r < 16; ++r) { const int row = row0 + r;
;             if (sample && (r & 3) == 0) { const int b = (row - TP) >> 2; const float* sp = P.in[I_SCONV] + ((size_t)(L * 32 + b) * 2) * DFF + c0;
; #pragma unroll
;                 for (int q = 0; q < 2; ++q) { const f32x4 s0 = *(const f32x4*)(sp + 4 * q), s1 = *(const f32x4*)(sp + DFF + 4 * q);
; #pragma unroll
;                     for (int j = 0; j < 4; ++j) { am2[4 * q + j] = s0[j]; am1[4 * q + j] = s1[j]; } } }
;             const u32x4 aw = *(const u32x4*)(AB + (size_t)row * DFF + c0), gw = *(const u32x4*)(GB + (size_t)row * DFF + c0);
.Lcv_wait_done:
	ds_read_b128 v[4:7], v94
	ds_read_b128 v[80:83], v94 offset:1024
	s_cmp_lt_u32 s24, 8
	s_cbranch_scc0 .Lcv_no_dma
	v_readfirstlane_b32 s55, v90
	s_mov_b32 s56, 0x16000
	s_mov_b32 s57, 0
	v_lshl_add_u64 v[92:93], v[64:65], 0, s[56:57]
	s_add_i32 s55, s55, s54
	s_mov_b32 s56, 0x5ac0000
	s_waitcnt lgkmcnt(0)
	s_mov_b32 m0, s55
	s_nop 0
	global_load_lds_dwordx4 v[92:93], off nt
	v_lshl_add_u64 v[92:93], v[92:93], 0, s[56:57]
	s_add_i32 m0, s55, 0x400
	s_nop 0
	global_load_lds_dwordx4 v[92:93], off nt
